# v26 + s_waitcnt vmcnt(24) before the 32 gain loads of the two conversion loops so that no more than 56 vector-memory operations are ever outstanding
# speedup vs baseline: 1.0016x; 1.0016x over previous
; __device__ __forceinline__ void conv_matrix(const float* W, int K, int N, bf16* WT, const float* sk, const float* sn, int mode, LAS float* scr, int lane, int gw, int NGW) {
;     ...
;     for (; it < nitems; it += NGW) {
;         const int kb = it / nblk, nb = it - kb * nblk, n0 = 32 * nb, k0 = 64 * kb; int drow0 = n0;
;         if (mode == 1) drow0 = n0 < DFF ? 256 * (n0 >> 7) + (n0 & 127) : 256 * ((n0 - DFF) >> 7) + 128 + ((n0 - DFF) & 127);
; #pragma unroll
;         for (int i = 0; i < 32; ++i) { const int kk = 2 * i + (lane >> 5); float t = v[i]; if (sk) t *= sk[k0 + kk]; scr[kk * 33 + (lane & 31)] = t; }
.LBB0_11:
	s_mul_hi_i32 s0, s80, 0x4ec4ec4f
	s_lshr_b32 s1, s0, 31
	s_ashr_i32 s81, s0, 7
	s_add_i32 s81, s81, s1
	s_lshl_b32 s0, s81, 6
	s_and_b64 vcc, exec, s[4:5]
	s_cbranch_vccnz .Lgn_skip_0
	s_waitcnt vmcnt(24)
	s_ashr_i32 s1, s0, 31
	v_lshl_add_u64 v[92:93], s[0:1], 0, v[36:37]
	v_lshl_add_u64 v[92:93], v[92:93], 2, s[38:39]
	global_load_dword v94, v[92:93], off
	global_load_dword v95, v[92:93], off offset:8
	global_load_dword v96, v[92:93], off offset:16
	global_load_dword v97, v[92:93], off offset:24
	global_load_dword v98, v[92:93], off offset:32
	global_load_dword v99, v[92:93], off offset:40
	global_load_dword v100, v[92:93], off offset:48
	global_load_dword v101, v[92:93], off offset:56
	global_load_dword v102, v[92:93], off offset:64
	global_load_dword v103, v[92:93], off offset:72
	global_load_dword v104, v[92:93], off offset:80
	global_load_dword v105, v[92:93], off offset:88
	global_load_dword v106, v[92:93], off offset:96
	global_load_dword v107, v[92:93], off offset:104
	global_load_dword v108, v[92:93], off offset:112
	global_load_dword v109, v[92:93], off offset:120
	global_load_dword v110, v[92:93], off offset:128
	global_load_dword v111, v[92:93], off offset:136
	global_load_dword v112, v[92:93], off offset:144
	global_load_dword v113, v[92:93], off offset:152
	global_load_dword v114, v[92:93], off offset:160
	global_load_dword v115, v[92:93], off offset:168
	global_load_dword v116, v[92:93], off offset:176
	global_load_dword v117, v[92:93], off offset:184
	global_load_dword v118, v[92:93], off offset:192
	global_load_dword v119, v[92:93], off offset:200
	global_load_dword v120, v[92:93], off offset:208
	global_load_dword v121, v[92:93], off offset:216
	global_load_dword v122, v[92:93], off offset:224
	global_load_dword v123, v[92:93], off offset:232
	global_load_dword v124, v[92:93], off offset:240
	global_load_dword v125, v[92:93], off offset:248

; __device__ __forceinline__ void conv_matrix(const float* W, int K, int N, bf16* WT, const float* sk, const float* sn, int mode, LAS float* scr, int lane, int gw, int NGW) {
;     ...
;     for (; it < nitems; it += NGW) {
;         const int kb = it / nblk, nb = it - kb * nblk, n0 = 32 * nb, k0 = 64 * kb; int drow0 = n0;
;         if (mode == 1) drow0 = n0 < DFF ? 256 * (n0 >> 7) + (n0 & 127) : 256 * ((n0 - DFF) >> 7) + 128 + ((n0 - DFF) & 127);
; #pragma unroll
;         for (int i = 0; i < 32; ++i) { const int kk = 2 * i + (lane >> 5); float t = v[i]; if (sk) t *= sk[k0 + kk]; scr[kk * 33 + (lane & 31)] = t; }
.LBB0_310:
	v_cndmask_b32_e64 v43, 0, 1, s[0:1]
	s_lshl_b32 s6, s6, 6
	v_cmp_ne_u32_e64 s[4:5], 1, v43
	s_andn2_b64 vcc, exec, s[0:1]
	s_cbranch_vccnz .Lgn_skip_1
	s_waitcnt vmcnt(24)
	s_ashr_i32 s7, s6, 31
	v_lshl_add_u64 v[216:217], s[6:7], 0, v[194:195]
	v_lshl_add_u64 v[216:217], v[216:217], 2, s[20:21]
	global_load_dword v218, v[216:217], off
	global_load_dword v219, v[216:217], off offset:8
	global_load_dword v220, v[216:217], off offset:16
	global_load_dword v221, v[216:217], off offset:24
	global_load_dword v223, v[216:217], off offset:32
	global_load_dword v224, v[216:217], off offset:40
	global_load_dword v225, v[216:217], off offset:48
	global_load_dword v226, v[216:217], off offset:56
	global_load_dword v227, v[216:217], off offset:64
	global_load_dword v228, v[216:217], off offset:72
	global_load_dword v229, v[216:217], off offset:80
	global_load_dword v230, v[216:217], off offset:88
	global_load_dword v231, v[216:217], off offset:96
	global_load_dword v232, v[216:217], off offset:104
	global_load_dword v233, v[216:217], off offset:112
	global_load_dword v234, v[216:217], off offset:120
	global_load_dword v235, v[216:217], off offset:128
	global_load_dword v236, v[216:217], off offset:136
	global_load_dword v237, v[216:217], off offset:144
	global_load_dword v238, v[216:217], off offset:152
	global_load_dword v239, v[216:217], off offset:160
	global_load_dword v240, v[216:217], off offset:168
	global_load_dword v241, v[216:217], off offset:176
	global_load_dword v242, v[216:217], off offset:184
	global_load_dword v243, v[216:217], off offset:192
	global_load_dword v244, v[216:217], off offset:200
	global_load_dword v245, v[216:217], off offset:208
	global_load_dword v247, v[216:217], off offset:216
	global_load_dword v248, v[216:217], off offset:224
	global_load_dword v249, v[216:217], off offset:232
	global_load_dword v250, v[216:217], off offset:240
	global_load_dword v251, v[216:217], off offset:248
